# v15 + MLA K-tile LDS swizzle widened to 4 row bits (ds_read_b128 of the 256-B K rows was 2-way bank conflicted)
# speedup vs baseline: 1.0113x; 1.0024x over previous
; template <int MODE> ...
;   int tid = threadIdx.x; asm volatile("" : "+v"(tid));
;   const int wid = __builtin_amdgcn_readfirstlane(tid >> 6), lane = tid & 63, r32 = lane & 31, hi = lane >> 5;
;   char* V_lds = lds + OFF_V; char* K_lds = lds + OFF_K; char* K2_lds = lds + OFF_K2;
;   float* ws = (float*)(lds + OFF_WS) + wid * 64; float* li_l = ws; float* al_l = ws + 32;
;   float* tb = (float*)(lds + OFF_TB);
;   int jlo = 0, jhi = NT - 1;
;   if constexpr (MODE == 1) { const int cq = qc0 + (wid >> 1); jlo = (cq - 8 > 0 ? cq - 8 : 0) - kc0; jhi = cq - kc0; }
;   if constexpr (MODE == 2) { jhi = qc0 + (wid >> 1) - kc0; }
;   if constexpr (MODE == 1) { if (tid < 257) tb[tid] = bias_g[tid] * 1.4426950408889634f; }
;   float m_reg = -1e30f, l_reg = 0; f32x16 o[4] = {}; bf16x8 qr[8];
;   char* Q2s = (MODE == 1) ? lds + OFF_Q1 + wid * 8192 : lds + OFF_Q2 + wid * 4096;
;   char* QHs = lds + OFF_QH + wid * 4096; char* Q3s = lds + OFF_Q3 + wid * 1024 + lane * 16;
;   const bf16_t* Qw = Qb + (long)(wid * QBLK + r32) * ldq + hi * 8;
;   if constexpr (MODE == 1) {
; #pragma unroll
;     for (int d0 = 0; d0 < 8; ++d0) *reinterpret_cast<bf16x8*>(Q2s + KSWZ(r32, (d0 * 16 + hi * 8) * 2)) = *reinterpret_cast<const bf16x8*>(Qw + d0 * 16);
;     asm volatile("s_waitcnt lgkmcnt(0)" ::: "memory");
;   } else if constexpr (MODE == 2) {
; #pragma unroll
;     for (int d0 = 0; d0 < 3; ++d0) qr[d0] = *reinterpret_cast<const bf16x8*>(Qw + d0 * 16);
;     *reinterpret_cast<bf16x8*>(Q3s) = *reinterpret_cast<const bf16x8*>(Qw + 3 * 16);
; #pragma unroll
;     for (int d0 = 4; d0 < 8; ++d0) *reinterpret_cast<bf16x8*>(QHs + K2SWZ(r32, ((d0 - 4) * 16 + hi * 8) * 2)) = *reinterpret_cast<const bf16x8*>(Qw + d0 * 16);
;     asm volatile("s_waitcnt lgkmcnt(0)" ::: "memory");
;   } else {
; #pragma unroll
;     for (int d0 = 0; d0 < 8; ++d0) qr[d0] = *reinterpret_cast<const bf16x8*>(Qw + d0 * 16);
;   }
;   if constexpr (MODE == 2) { const bf16_t* Q2w = Q2b + (long)(wid * QBLK + r32) * ldq2 + hi * 8;
; #pragma unroll
;     for (int d0 = 0; d0 < 4; ++d0) *reinterpret_cast<bf16x8*>(Q2s + K2SWZ(r32, (d0 * 16 + hi * 8) * 2)) = *reinterpret_cast<const bf16x8*>(Q2w + d0 * 16);
;     asm volatile("s_waitcnt lgkmcnt(0)" ::: "memory"); }
;   const int sr = tid >> 4, sc = (tid & 15) * 8, vst0 = v_st(sr, sc), vst1 = v_st(32 + sr, sc);
;   const int s2r = tid >> 3, s2c = (tid & 7) * 8;
.LBB0_270:
	s_and_b64 vcc, exec, s[4:5]
	s_cbranch_vccz .LBB0_206
	s_lshl_b32 s2, s35, 7
	s_and_b32 s24, s2, 0x180000
	s_lshl_b32 s2, s35, 12
	s_and_b32 s38, s2, 0x3000000
	s_and_b32 s2, s14, 1
	s_bfe_u32 s3, s54, 0x20006
	s_lshl_b32 s4, s3, 8
	s_lshl_b32 s2, s2, 10
	s_or_b32 s59, s2, s4
	s_bfe_u32 s4, s54, 0x30003
	s_lshl_b32 s2, s54, 2
	s_xor_b32 s5, s4, 15
	s_cmpk_lt_u32 s54, 0x100
	s_cselect_b32 s8, s5, s4
	s_and_b32 s2, s2, 4
	s_or_b32 s4, s2, s3
	s_lshl_b32 s2, s54, 11
	s_and_b32 s5, s2, 0x3000
	s_lshl_b32 s2, s8, 8
	s_or_b32 s3, s2, s5
	s_mul_i32 s2, s3, 0xc00
	v_readlane_b32 s6, v251, 54
	v_readlane_b32 s7, v251, 55
	s_add_u32 s6, s6, s2
	s_addc_u32 s7, s7, 0
	s_lshl_b32 s2, s4, 7
	s_lshl_b32 s4, s4, 8
	s_add_u32 s10, s6, s4
	s_addc_u32 s11, s7, 0
	s_add_u32 s6, s6, s2
	s_addc_u32 s7, s7, 0
	s_lshl_b32 s9, s5, 12
	v_readlane_b32 s12, v251, 56
	v_readlane_b32 s13, v251, 57
	s_add_u32 s9, s12, s9
	s_addc_u32 s12, s13, 0
	s_add_u32 s36, s9, s4
	s_addc_u32 s37, s12, 0
	s_add_u32 s52, s36, 0x800
	s_addc_u32 s53, s37, 0
	s_lshl_b32 s4, s5, 7
	v_readlane_b32 s12, v250, 0
	v_mov_b32_e32 v58, v198
	v_readlane_b32 s13, v250, 1
	s_add_u32 s4, s12, s4
	s_addc_u32 s5, s13, 0
	v_readfirstlane_b32 s9, v58
	s_ashr_i32 s12, s9, 6
	v_and_b32_e32 v1, 31, v58
	s_lshl_b32 s40, s12, 5
	v_bfe_u32 v118, v58, 5, 1
	v_or_b32_e32 v5, s40, v1
	v_mov_b64_e32 v[2:3], s[10:11]
	s_movk_i32 s13, 0xc00
	v_mad_i64_i32 v[2:3], s[10:11], v5, s13, v[2:3]
	v_lshlrev_b32_e32 v174, 4, v118
	v_lshl_add_u64 v[2:3], v[2:3], 0, v[174:175]
	global_load_dwordx4 v[6:9], v[2:3], off offset:96
	global_load_dwordx4 v[10:13], v[2:3], off offset:128
	global_load_dwordx4 v[14:17], v[2:3], off offset:160
	global_load_dwordx4 v[18:21], v[2:3], off offset:192
	global_load_dwordx4 v[22:25], v[2:3], off offset:224
	v_mov_b64_e32 v[26:27], s[6:7]
	s_lshl_b32 s6, s12, 12
	v_lshlrev_b32_e32 v34, 3, v58
	s_movk_i32 s10, 0x70
	s_lshl_b32 s7, s12, 10
	s_add_i32 s12, s6, 0
	v_and_b32_e32 v59, 63, v58
	v_lshlrev_b32_e32 v70, 7, v1
	v_and_b32_e32 v4, 0x70, v34
	v_bitop3_b32 v35, v174, v34, s10 bitop3:0x78
	s_movk_i32 s10, 0x60
	s_add_i32 s7, s7, 0
	s_add_i32 s6, s12, 0x1d000
	v_lshlrev_b32_e32 v61, 4, v59
	v_bitop3_b32 v36, v174, v4, 32 bitop3:0x36
	v_bitop3_b32 v37, v174, v4, 64 bitop3:0x36
	v_bitop3_b32 v38, v174, v4, s10 bitop3:0x36
	s_add_i32 s7, s7, 0x25000
	v_mad_i64_i32 v[26:27], s[10:11], v5, s13, v[26:27]
	v_add_u32_e32 v5, s6, v70
	v_add_u32_e32 v122, s7, v61
	global_load_dwordx4 v[106:109], v[2:3], off
	global_load_dwordx4 v[102:105], v[2:3], off offset:32
	global_load_dwordx4 v[98:101], v[2:3], off offset:64
	v_add_u32_e32 v2, v5, v35
	v_add_u32_e32 v3, v5, v36
	v_add_u32_e32 v28, v5, v37
	v_add_u32_e32 v5, v5, v38
	v_lshl_add_u64 v[26:27], v[26:27], 0, v[174:175]
	s_add_i32 s65, s12, 0x15000
	s_mov_b64 s[10:11], 0x20000
	v_lshlrev_b32_e32 v71, 8, v1
	s_ashr_i32 s23, s9, 7
	v_or_b32_e32 v72, 32, v1
	v_lshlrev_b32_e32 v74, 8, v72
	v_or_b32_e32 v73, 32, v174
	v_bitop3_b32 v144, v174, v70, v4 bitop3:0xde
	v_add_u32_e32 v138, s6, v144
	v_bitop3_b32 v150, v73, v70, v4 bitop3:0xde
	v_add_u32_e32 v141, s6, v150
	v_add_u32_e32 v149, s65, v144
	v_add_u32_e32 v152, s65, v150
	s_mov_b32 s7, s25
	s_mov_b32 s12, s25
	s_mov_b32 s13, s25
	s_mov_b32 s14, s25
	s_mov_b32 s15, s25
	s_mov_b32 s16, s25
	s_mov_b32 s17, s25
	s_mov_b32 s18, s25
	v_lshlrev_b32_e32 v78, 1, v58
	v_lshlrev_b32_e32 v79, 3, v59
	v_and_b32_e32 v61, 0xc0, v61
	v_and_b32_e32 v78, 32, v78
	v_and_b32_e32 v80, 0x100, v79
	v_and_or_b32 v61, v79, 24, v61
	v_or3_b32 v61, v61, v78, v80
	s_mov_b32 s39, s25
	s_mov_b32 s55, 2
	v_mov_b32_e32 v120, 0
	s_waitcnt vmcnt(0)
	ds_write_b128 v122, v[6:9]
	s_waitcnt vmcnt(6)
	ds_write_b128 v2, v[10:13]
	s_waitcnt vmcnt(5)
	ds_write_b128 v3, v[14:17]
	s_waitcnt vmcnt(4)
	ds_write_b128 v28, v[18:21]
	s_waitcnt vmcnt(3)
	ds_write_b128 v5, v[22:25]
	s_waitcnt lgkmcnt(0)
	global_load_dwordx4 v[6:9], v[26:27], off offset:2048
	global_load_dwordx4 v[10:13], v[26:27], off offset:2080
	global_load_dwordx4 v[14:17], v[26:27], off offset:2112
	global_load_dwordx4 v[18:21], v[26:27], off offset:2144
	v_ashrrev_i32_e32 v28, 3, v58
	v_ashrrev_i32_e32 v29, 31, v28
	v_ashrrev_i32_e32 v26, 4, v58
	v_lshlrev_b32_e32 v2, 4, v58
	v_and_b32_e32 v244, 0xf0, v2
	v_lshlrev_b64 v[52:53], 7, v[28:29]
	v_mov_b32_e32 v3, v175
	v_and_b32_e32 v5, 0x78, v34
	v_ashrrev_i32_e32 v27, 31, v26
	v_and_b32_e32 v2, 0x70, v2
	v_lshl_add_u64 v[32:33], s[4:5], 0, v[52:53]
	v_lshlrev_b32_e32 v5, 1, v5
	v_lshlrev_b64 v[50:51], 12, v[26:27]
	v_lshl_add_u64 v[54:55], v[32:33], 0, v[2:3]
	v_add_u32_e32 v3, s65, v70
	v_or_b32_e32 v56, v50, v5
	v_mov_b32_e32 v57, v51
	v_add_u32_e32 v27, v3, v35
	v_add_u32_e32 v29, v3, v36
	v_add_u32_e32 v32, v3, v37
	v_add_u32_e32 v3, v3, v38
	v_lshl_add_u64 v[22:23], v[56:57], 0, s[10:11]
	v_lshl_add_u64 v[24:25], s[36:37], 0, v[56:57]
	v_lshl_add_u64 v[30:31], s[36:37], 0, v[22:23]
	v_lshl_add_u64 v[22:23], s[52:53], 0, v[22:23]
	v_add_u32_e32 v33, 32, v26
	v_lshlrev_b32_e32 v28, 7, v28
	s_and_b32 s5, s9, 0x3fffffc0
	s_lshl_b32 s5, s5, 2
	s_lshl_b32 s4, s8, 2
	s_add_i32 s22, s5, 0
	s_add_i32 s33, s4, 4
	s_add_i32 s41, s23, s4
	s_add_i32 s22, s22, 0x10000
	s_cmp_lg_u32 0, -1
	s_cselect_b32 s61, 0, 0
	s_add_i32 s19, 0, 0x11000
	v_add_u32_e32 v155, s19, v144
	v_add_u32_e32 v158, s19, v150
	s_cmp_gt_i32 s41, -1
	s_cselect_b64 vcc, -1, 0
	s_mov_b32 s4, s25
	s_mov_b32 s5, s25
	s_mov_b32 s8, s25
	s_mov_b32 s9, s25
	s_mov_b32 s10, s25
	s_mov_b32 s11, s25
	v_lshl_add_u64 v[110:111], s[24:25], 0, v[52:53]
	v_add_u32_e32 v137, s61, v61
	v_lshl_add_u64 v[112:113], s[38:39], 0, v[50:51]
	v_lshl_add_u32 v119, v1, 2, s22
	s_waitcnt vmcnt(3)
; #define KFRAG(d, hf) (((d) < 8) ? *reinterpret_cast<const bf16x8*>(Ks + KSWZ((hf) * 32 + r32, ((d) * 16 + hi * 8) * 2)) \
;                                 : *reinterpret_cast<const bf16x8*>(K2s + K2SWZ((hf) * 32 + r32, (((d) - 8) * 16 + hi * 8) * 2)))
; #define QLDS(d) (((d) == 3) ? *reinterpret_cast<const bf16x8*>(Q3s) : ((d) < 8) ? *reinterpret_cast<const bf16x8*>(QHs + K2SWZ(r32, (((d) - 4) * 16 + hi * 8) * 2)) \
;                            : *reinterpret_cast<const bf16x8*>(Q2s + K2SWZ(r32, (((d) - 8) * 16 + hi * 8) * 2)))
; __device__ __forceinline__ int v_st(int k, int c) { const int kk = (k & ~0xC) | ((k & 4) << 1) | ((k & 8) >> 1); return ((kk >> 3) * 4 + (c >> 5)) * 512 + ((kk & 7) * 32 + (c & 31)) * 2; }
; __device__ __forceinline__ int v_rd_base(int lane) { return ((lane & 3) << 3) | (((lane >> 2) & 3) << 6) | (((lane >> 4) & 1) << 5) | (((lane >> 5) & 1) << 8); }
; template <int MODE>
; __device__ __forceinline__ void qkt(f32x16& p0, f32x16& p1, const char* Ks, const char* K2s, const bf16x8* qr, const char* Q2s, const char* QHs, const char* Q3s, int r32, int hi, bool valid) {
;     ...
;     p0 = f32x16{}; p1 = f32x16{};
;     constexpr int ND = (MODE == 2) ? 12 : 8;
;     bf16x8 ka[2], kb[2];
;     ka[0] = KFRAG(0, 0); kb[0] = KFRAG(0, 1);
; #pragma unroll
;     for (int d = 0; d < ND; ++d) {
;       bf16x8 q; if (MODE == 2 && d >= 3) q = QLDS(d); else q = qr[d < 8 ? d : 0];
;       if (d + 1 < ND) { ka[(d + 1) & 1] = KFRAG(d + 1, 0); kb[(d + 1) & 1] = KFRAG(d + 1, 1); }
;       p0 = __builtin_amdgcn_mfma_f32_32x32x16_bf16(ka[d & 1], q, p0, 0, 0, 0);
;       p1 = __builtin_amdgcn_mfma_f32_32x32x16_bf16(kb[d & 1], q, p1, 0, 0, 0);
;     }
; template <int MODE> ...
;     ...
;   const int sr = tid >> 4, sc = (tid & 15) * 8, vst0 = v_st(sr, sc), vst1 = v_st(32 + sr, sc);
;   const int s2r = tid >> 3, s2c = (tid & 7) * 8;
;   const int vb0 = (int)(uintptr_t)V_lds + v_rd_base(lane);
;   const int relq = (qc0 - kc0) * 64 + wid * 32 + r32 - 4 * hi;
;   struct { bf16x8 vs0, vs1, ks0, ks1, k2; } sr_[SDEPTH];
;     ...
;   f32x16 pA0, pA1, pB0, pB1; float mnA, mnB, alA, alB; bf16x8 pa0, pa1, pa2, pa3;
;   constexpr int SE = 0, SO = SDEPTH - 1;
;   SLOAD(SE, 0); asm volatile("s_waitcnt vmcnt(0)" ::: "memory"); SWRITE(0, SE); __syncthreads();
;   QKT(pA0, pA1, 0, 0); partialSM(pA0, pA1, m_reg, mnA, alA);
	ds_write_b128 v27, v[6:9]
	s_waitcnt vmcnt(2)
	ds_write_b128 v29, v[10:13]
	s_waitcnt vmcnt(1)
	ds_write_b128 v32, v[14:17]
	s_waitcnt vmcnt(0)
	ds_write_b128 v3, v[18:21]
	s_waitcnt lgkmcnt(0)
	global_load_dwordx4 v[6:9], v[24:25], off offset:2048
	global_load_dwordx4 v[10:13], v[22:23], off
	global_load_dwordx4 v[14:17], v[24:25], off
	global_load_dwordx4 v[18:21], v[30:31], off
	v_and_b32_e32 v27, 0xfffff0, v26
	global_load_dwordx4 v[22:25], v[54:55], off
	v_lshlrev_b32_e32 v29, 1, v26
	v_lshrrev_b32_e32 v30, 1, v26
	v_and_b32_e32 v32, 3, v26
	v_and_b32_e32 v3, 0x70, v58
	v_and_b32_e32 v245, 0xf0, v58
	v_and_or_b32 v27, v29, 8, v27
	v_and_or_b32 v29, v30, 4, v32
	v_and_b32_e32 v30, 0xfffff0, v33
	v_lshlrev_b32_e32 v32, 1, v33
	v_lshlrev_b32_e32 v26, 8, v26
	v_bitop3_b32 v60, v2, v28, v3 bitop3:0xde
	v_bitop3_b32 v28, v174, v71, v244 bitop3:0xde
	v_and_or_b32 v30, v32, 8, v30
	v_bfe_u32 v31, v34, 5, 2
	v_lshlrev_b32_e32 v33, 8, v33
	v_lshrrev_b32_e32 v27, 1, v27
	v_bitop3_b32 v26, v5, v26, v245 bitop3:0xde
	v_add_u32_e32 v123, 0, v28
	v_lshrrev_b32_e32 v28, 1, v30
	v_bitop3_b32 v3, v5, v33, v245 bitop3:0xde
	v_or_b32_e32 v27, v27, v31
	v_add_u32_e32 v124, 0, v26
	v_or_b32_e32 v26, v28, v31
	v_lshlrev_b32_e32 v29, 6, v29
	v_and_b32_e32 v34, 48, v5
	v_add_u32_e32 v125, 0, v3
	v_lshlrev_b32_e32 v3, 9, v27
	v_lshlrev_b32_e32 v26, 9, v26
	v_or3_b32 v3, v3, v29, v34
	v_or3_b32 v26, v26, v29, v34
	v_add_u32_e32 v126, 0, v3
	v_add_u32_e32 v127, 0, v26
	v_add_u32_e32 v3, s19, v60
	s_waitcnt vmcnt(0)
	v_bitop3_b32 v5, v174, v74, v244 bitop3:0xde
	v_add_u32_e32 v128, 0, v5
	v_add_u32_e32 v169, 0, v60
	v_add_u32_e32 v170, 0x13000, v169
	s_waitcnt vmcnt(4)
	ds_write_b128 v126, v[6:9]
	s_waitcnt vmcnt(3)
	ds_write_b128 v127, v[10:13]
	s_waitcnt vmcnt(2)
	ds_write_b128 v124, v[14:17] offset:32768
	s_waitcnt vmcnt(1)
	ds_write_b128 v125, v[18:21] offset:32768
	v_bitop3_b32 v10, v73, v74, v244 bitop3:0xde
	s_waitcnt vmcnt(0)
	ds_write_b128 v3, v[22:25]
	s_waitcnt lgkmcnt(0)
	s_barrier
	ds_read_b128 v[6:9], v123 offset:32768
	v_add_u32_e32 v130, 0, v10
	ds_read_b128 v[10:13], v128 offset:32768
	v_bitop3_b32 v3, v73, v71, v244 bitop3:0xde
	v_add_u32_e32 v129, 0, v3
	ds_read_b128 v[14:17], v129 offset:32768
	ds_read_b128 v[62:65], v130 offset:32768
	s_waitcnt lgkmcnt(3)
	v_mfma_f32_32x32x16_bf16 v[18:33], v[6:9], v[106:109], 0
	v_or_b32_e32 v3, 64, v174
	v_bitop3_b32 v5, v3, v71, v244 bitop3:0xde
	v_bitop3_b32 v6, v3, v74, v244 bitop3:0xde
	v_add_u32_e32 v131, 0, v5
	v_add_u32_e32 v132, 0, v6
	v_or_b32_e32 v5, 0x60, v174
	v_bitop3_b32 v151, v3, v70, v4 bitop3:0xde
	s_waitcnt lgkmcnt(2)
	v_mfma_f32_32x32x16_bf16 v[34:49], v[10:13], v[106:109], 0
	ds_read_b128 v[6:9], v131 offset:32768
	ds_read_b128 v[10:13], v132 offset:32768
	v_add_u32_e32 v145, s6, v151
	v_bitop3_b32 v153, v5, v70, v4 bitop3:0xde
	v_add_u32_e32 v148, s6, v153
	v_add_u32_e32 v163, s19, v151
	v_add_u32_e32 v160, s65, v151
	s_waitcnt lgkmcnt(3)
	v_mfma_f32_32x32x16_bf16 v[18:33], v[14:17], v[102:105], v[18:33]
	v_bitop3_b32 v14, v5, v71, v244 bitop3:0xde
	v_bitop3_b32 v15, v5, v74, v244 bitop3:0xde
	v_add_u32_e32 v133, 0, v14
	v_add_u32_e32 v134, 0, v15
	v_add_u32_e32 v166, s19, v153
	v_add_u32_e32 v161, s65, v153
	s_mov_b32 s6, s25
	s_waitcnt lgkmcnt(2)
	v_mfma_f32_32x32x16_bf16 v[34:49], v[62:65], v[102:105], v[34:49]
	ds_read_b128 v[14:17], v133 offset:32768
	ds_read_b128 v[62:65], v134 offset:32768
	s_movk_i32 s65, 0x2000
	s_waitcnt lgkmcnt(3)
	v_mfma_f32_32x32x16_bf16 v[18:33], v[6:9], v[98:101], v[18:33]
	v_or_b32_e32 v6, 0x80, v174
	s_waitcnt lgkmcnt(2)
	v_mfma_f32_32x32x16_bf16 v[34:49], v[10:13], v[98:101], v[34:49]
	v_bitop3_b32 v10, v6, v71, v244 bitop3:0xde
	v_bitop3_b32 v11, v6, v74, v244 bitop3:0xde
	ds_read_b128 v[6:9], v122
	v_add_u32_e32 v135, 0, v10
	v_add_u32_e32 v136, 0, v11
	ds_read_b128 v[10:13], v135 offset:32768
	ds_read_b128 v[66:69], v136 offset:32768
	s_waitcnt lgkmcnt(2)
	v_mfma_f32_32x32x16_bf16 v[18:33], v[14:17], v[6:9], v[18:33]
	v_or_b32_e32 v14, 0xa0, v174
	v_bitop3_b32 v15, v14, v71, v244 bitop3:0xde
	v_bitop3_b32 v14, v14, v74, v244 bitop3:0xde
	v_add_u32_e32 v139, 0, v15
	v_add_u32_e32 v140, 0, v14
	v_mfma_f32_32x32x16_bf16 v[34:49], v[62:65], v[6:9], v[34:49]
	ds_read_b128 v[6:9], v138
	ds_read_b128 v[14:17], v139 offset:32768
	ds_read_b128 v[62:65], v140 offset:32768
	s_waitcnt lgkmcnt(2)
	v_mfma_f32_32x32x16_bf16 v[18:33], v[10:13], v[6:9], v[18:33]
	v_or_b32_e32 v10, 0xc0, v174
	v_bitop3_b32 v11, v10, v71, v244 bitop3:0xde
	v_bitop3_b32 v10, v10, v74, v244 bitop3:0xde
	v_add_u32_e32 v142, 0, v11
	v_add_u32_e32 v143, 0, v10
	v_mfma_f32_32x32x16_bf16 v[34:49], v[66:69], v[6:9], v[34:49]
	ds_read_b128 v[6:9], v141
	ds_read_b128 v[10:13], v142 offset:32768
	ds_read_b128 v[66:69], v143 offset:32768
	s_waitcnt lgkmcnt(2)
	v_mfma_f32_32x32x16_bf16 v[18:33], v[14:17], v[6:9], v[18:33]
	v_or_b32_e32 v14, 0xe0, v174
	v_bitop3_b32 v15, v14, v71, v244 bitop3:0xde
	v_bitop3_b32 v2, v14, v74, v244 bitop3:0xde
	v_add_u32_e32 v146, 0, v15
	v_add_u32_e32 v147, 0, v2
	v_lshlrev_b32_e32 v2, 7, v72
	v_bitop3_b32 v154, v174, v2, v4 bitop3:0xde
	v_mfma_f32_32x32x16_bf16 v[34:49], v[62:65], v[6:9], v[34:49]
	ds_read_b128 v[6:9], v145
	ds_read_b128 v[14:17], v146 offset:32768
	ds_read_b128 v[62:65], v147 offset:32768
	v_add_u32_e32 v156, s19, v154
	v_bitop3_b32 v157, v73, v2, v4 bitop3:0xde
	v_add_u32_e32 v159, s19, v157
	v_bitop3_b32 v162, v3, v2, v4 bitop3:0xde
	s_waitcnt lgkmcnt(2)
	v_mfma_f32_32x32x16_bf16 v[18:33], v[10:13], v[6:9], v[18:33]
	v_add_u32_e32 v164, s19, v162
	v_bitop3_b32 v165, v5, v2, v4 bitop3:0xde
	v_add_u32_e32 v167, s19, v165
	s_mov_b32 s19, s25
	v_mfma_f32_32x32x16_bf16 v[34:49], v[66:69], v[6:9], v[34:49]
	ds_read_b128 v[6:9], v148
	ds_read_b128 v[10:13], v155
	ds_read_b128 v[66:69], v156
	s_waitcnt lgkmcnt(2)
; __device__ __forceinline__ void partialSM(f32x16& p0, f32x16& p1, float& m_reg, float& mn, float& alpha) {
;   float pmax = p0[0];
; #pragma unroll
;   for (int r = 1; r < 16; ++r) pmax = fmaxf(pmax, p0[r]);
; #pragma unroll
;   for (int r = 0; r < 16; ++r) pmax = fmaxf(pmax, p1[r]);
;   { auto rr = __builtin_amdgcn_permlane32_swap(__float_as_uint(pmax), __float_as_uint(pmax), false, false);
;     pmax = fmaxf(__uint_as_float(rr[0]), __uint_as_float(rr[1])); }
;   if (__builtin_expect(__all(pmax - m_reg <= THR), 1)) { mn = m_reg; alpha = 1.f; }
;   else { mn = fmaxf(m_reg, pmax); alpha = __builtin_amdgcn_exp2f(m_reg - mn); m_reg = mn; }
; #pragma unroll
;   for (int r = 0; r < 16; ++r) p0[r] = p0[r] - mn;
; #pragma unroll
;   for (int r = 0; r < 16; ++r) p1[r] = p1[r] - mn;
; #pragma unroll
;   for (int r = 0; r < 16; ++r) p0[r] = __builtin_amdgcn_exp2f(p0[r]);
; template <int MODE>
; __device__ __forceinline__ void qkt(f32x16& p0, f32x16& p1, const char* Ks, const char* K2s, const bf16x8* qr, const char* Q2s, const char* QHs, const char* Q3s, int r32, int hi, bool valid) {
;     ...
;     p0 = f32x16{}; p1 = f32x16{};
;     constexpr int ND = (MODE == 2) ? 12 : 8;
;     bf16x8 ka[2], kb[2];
;     ka[0] = KFRAG(0, 0); kb[0] = KFRAG(0, 1);
; #pragma unroll
;     for (int d = 0; d < ND; ++d) {
;       bf16x8 q; if (MODE == 2 && d >= 3) q = QLDS(d); else q = qr[d < 8 ? d : 0];
;       if (d + 1 < ND) { ka[(d + 1) & 1] = KFRAG(d + 1, 0); kb[(d + 1) & 1] = KFRAG(d + 1, 1); }
;       p0 = __builtin_amdgcn_mfma_f32_32x32x16_bf16(ka[d & 1], q, p0, 0, 0, 0);
;       p1 = __builtin_amdgcn_mfma_f32_32x32x16_bf16(kb[d & 1], q, p1, 0, 0, 0);
;     }
;     __builtin_amdgcn_sched_group_barrier(0x100, 2, 0);
; #pragma unroll
;     for (int d = 0; d < ND; ++d) {
;       { const int nrd = ((MODE == 2 && d >= 3) ? 1 : 0) + ((d + 1 < ND) ? 2 : 0);
;         if (nrd == 3) __builtin_amdgcn_sched_group_barrier(0x100, 3, 0); else if (nrd == 2) __builtin_amdgcn_sched_group_barrier(0x100, 2, 0); else if (nrd == 1) __builtin_amdgcn_sched_group_barrier(0x100, 1, 0); }
;       __builtin_amdgcn_sched_group_barrier(0x008, 2, 0);
;     }
;     if constexpr (MODE == 2) {
;       const float msk = valid ? 0.f : -INFINITY;
; #pragma unroll
;       for (int r = 0; r < 16; ++r) { p0[r] = valid ? p0[r] : msk; p1[r] = valid ? p1[r] : msk; }
;     }
	v_mfma_f32_32x32x16_bf16 v[18:33], v[14:17], v[6:9], v[18:33]
	v_mfma_f32_32x32x16_bf16 v[34:49], v[62:65], v[6:9], v[34:49]
	ds_read_b128 v[6:9], v149
	ds_read_b128 v[14:17], v158
	ds_read_b128 v[62:65], v159
	s_waitcnt lgkmcnt(2)
	v_mfma_f32_32x32x16_bf16 v[18:33], v[10:13], v[6:9], v[18:33]
	v_mfma_f32_32x32x16_bf16 v[34:49], v[66:69], v[6:9], v[34:49]
	ds_read_b128 v[6:9], v152
	ds_read_b128 v[10:13], v163
	ds_read_b128 v[66:69], v164
	s_waitcnt lgkmcnt(2)
	v_mfma_f32_32x32x16_bf16 v[18:33], v[14:17], v[6:9], v[18:33]
	v_mfma_f32_32x32x16_bf16 v[34:49], v[62:65], v[6:9], v[34:49]
	ds_read_b128 v[62:65], v160
	ds_read_b128 v[70:73], v166
	ds_read_b128 v[74:77], v167
	s_waitcnt lgkmcnt(2)
	v_mfma_f32_32x32x16_bf16 v[18:33], v[10:13], v[62:65], v[18:33]
	v_mov_b64_e32 v[2:3], s[4:5]
	v_mov_b64_e32 v[4:5], s[6:7]
	v_mov_b64_e32 v[6:7], s[8:9]
	v_mov_b64_e32 v[8:9], s[10:11]
	v_mov_b64_e32 v[10:11], s[12:13]
	v_mov_b64_e32 v[12:13], s[14:15]
	v_mov_b64_e32 v[14:15], s[16:17]
	v_mfma_f32_32x32x16_bf16 v[34:49], v[66:69], v[62:65], v[34:49]
	ds_read_b128 v[62:65], v161
	v_mov_b64_e32 v[16:17], s[18:19]
	s_mov_b64 s[4:5], 0x40000
	v_lshl_add_u64 v[66:67], v[56:57], 0, s[4:5]
	s_mov_b64 s[4:5], 0x60000
	v_lshl_add_u64 v[56:57], v[56:57], 0, s[4:5]
	v_lshl_add_u64 v[78:79], s[36:37], 0, v[66:67]
	s_waitcnt lgkmcnt(0)
	v_mfma_f32_32x32x16_bf16 v[18:33], v[70:73], v[62:65], v[18:33]
	v_lshl_add_u64 v[66:67], s[52:53], 0, v[66:67]
	v_lshl_add_u64 v[70:71], s[52:53], 0, v[56:57]
	global_load_dwordx4 v[66:69], v[66:67], off
	s_nop 0
	global_load_dwordx4 v[70:73], v[70:71], off
	s_nop 6
	v_cndmask_b32_e32 v80, v0, v26, vcc
	v_mfma_f32_32x32x16_bf16 v[34:49], v[74:77], v[62:65], v[34:49]
	v_cndmask_b32_e32 v62, v0, v18, vcc
	v_cndmask_b32_e32 v63, v0, v19, vcc
	v_max_f32_e32 v18, v63, v63
	v_max_f32_e32 v19, v62, v62
	v_cndmask_b32_e32 v64, v0, v20, vcc
	v_cndmask_b32_e32 v65, v0, v21, vcc
	v_max_f32_e32 v18, v19, v18
	v_cndmask_b32_e32 v74, v0, v22, vcc
	v_cndmask_b32_e32 v75, v0, v23, vcc
	v_max3_f32 v18, v18, v64, v65
	v_cndmask_b32_e32 v76, v0, v24, vcc
	v_cndmask_b32_e32 v77, v0, v25, vcc
	v_max3_f32 v18, v18, v74, v75
	v_cndmask_b32_e32 v81, v0, v27, vcc
	v_max3_f32 v18, v18, v76, v77
	v_cndmask_b32_e32 v82, v0, v28, vcc
	v_cndmask_b32_e32 v83, v0, v29, vcc
	v_max3_f32 v18, v18, v80, v81
	v_cndmask_b32_e32 v30, v0, v30, vcc
	v_cndmask_b32_e32 v31, v0, v31, vcc
	v_max3_f32 v18, v18, v82, v83
	v_max3_f32 v84, v18, v30, v31
	global_load_dwordx4 v[18:21], v[78:79], off
	v_cndmask_b32_e32 v34, v0, v34, vcc
	v_cndmask_b32_e32 v35, v0, v35, vcc
	v_cndmask_b32_e32 v36, v0, v36, vcc
	v_cndmask_b32_e32 v37, v0, v37, vcc
	v_cndmask_b32_e32 v38, v0, v38, vcc
	v_cndmask_b32_e32 v39, v0, v39, vcc
	v_cndmask_b32_e32 v40, v0, v40, vcc
	v_cndmask_b32_e32 v41, v0, v41, vcc
	v_cndmask_b32_e32 v42, v0, v42, vcc
	v_cndmask_b32_e32 v43, v0, v43, vcc
	v_cndmask_b32_e32 v44, v0, v44, vcc
	v_cndmask_b32_e32 v45, v0, v45, vcc
	v_cndmask_b32_e32 v46, v0, v46, vcc
	v_cndmask_b32_e32 v47, v0, v47, vcc
	v_cndmask_b32_e32 v32, v0, v32, vcc
	v_cndmask_b32_e32 v48, v0, v48, vcc
	v_cndmask_b32_e32 v33, v0, v33, vcc
	v_cndmask_b32_e32 v49, v0, v49, vcc
	v_add_co_u32_e32 v26, vcc, s65, v54
	v_lshl_add_u64 v[22:23], s[36:37], 0, v[56:57]
	s_nop 0
	v_addc_co_u32_e32 v27, vcc, 0, v55, vcc
	global_load_dwordx4 v[22:25], v[22:23], off
	v_max3_f32 v54, v84, v32, v33
	global_load_dwordx4 v[26:29], v[26:27], off
	v_max3_f32 v54, v54, v34, v35
	v_max3_f32 v54, v54, v36, v37
	v_max3_f32 v54, v54, v38, v39
	v_max3_f32 v54, v54, v40, v41
	v_max3_f32 v54, v54, v42, v43
	v_max3_f32 v54, v54, v44, v45
	v_max3_f32 v54, v54, v46, v47
	v_max3_f32 v54, v54, v48, v49
	v_mov_b32_e32 v55, v54
	s_nop 1
	v_permlane32_swap_b32_e32 v54, v55
	v_max_f32_e32 v55, v55, v55
	v_max_f32_e32 v54, v54, v54
	v_max_f32_e32 v54, v54, v55
	v_add_f32_e32 v55, 0x7149f2ca, v54
	v_max_f32_e32 v54, 0xf149f2ca, v54
	v_cmp_ge_f32_e32 vcc, s58, v55
	v_sub_f32_e32 v55, 0xf149f2ca, v54
	v_exp_f32_e32 v55, v55
	s_cmp_eq_u64 vcc, exec
	s_cselect_b64 vcc, -1, 0
	v_cndmask_b32_e32 v171, v54, v202, vcc
	v_cndmask_b32_e64 v168, v55, 1.0, vcc
	v_sub_f32_e32 v54, v62, v171
	v_sub_f32_e32 v55, v63, v171
	v_sub_f32_e32 v56, v64, v171
	v_sub_f32_e32 v57, v65, v171
	v_sub_f32_e32 v62, v74, v171
	v_sub_f32_e32 v63, v75, v171
	v_sub_f32_e32 v64, v76, v171
	v_sub_f32_e32 v65, v77, v171
	v_sub_f32_e32 v74, v80, v171
	v_sub_f32_e32 v75, v81, v171
	v_sub_f32_e32 v76, v82, v171
	v_sub_f32_e32 v77, v83, v171
	v_sub_f32_e32 v30, v30, v171
	v_sub_f32_e32 v31, v31, v171
	v_sub_f32_e32 v32, v32, v171
	v_sub_f32_e32 v33, v33, v171
	s_waitcnt vmcnt(0)
	s_waitcnt vmcnt(4)
	ds_write_b128 v126, v[66:69] offset:16384
	s_waitcnt vmcnt(3)
	ds_write_b128 v127, v[70:73] offset:16384
	v_exp_f32_e32 v220, v54
	v_exp_f32_e32 v221, v55
	v_exp_f32_e32 v222, v56
	v_exp_f32_e32 v223, v57
	v_exp_f32_e32 v224, v62
	v_exp_f32_e32 v225, v63
	v_exp_f32_e32 v226, v64
	v_exp_f32_e32 v227, v65
	v_exp_f32_e32 v115, v74
	v_exp_f32_e32 v116, v75
	v_exp_f32_e32 v117, v76
	s_waitcnt vmcnt(2)
	ds_write_b128 v124, v[18:21] offset:49152
	v_and_b32_e32 v18, 7, v58
	v_exp_f32_e32 v214, v77
	v_exp_f32_e32 v216, v30
	v_exp_f32_e32 v217, v31
	v_exp_f32_e32 v218, v32
	v_exp_f32_e32 v219, v33
	v_lshl_or_b32 v110, v18, 4, v110
	v_and_b32_e32 v18, 15, v58
	s_addk_i32 s61, 0x4000
	v_lshlrev_b32_e32 v18, 4, v18
	v_sub_f32_e32 v228, v34, v171
	v_sub_f32_e32 v229, v35, v171
	v_sub_f32_e32 v230, v36, v171
	v_sub_f32_e32 v231, v37, v171
	v_sub_f32_e32 v232, v38, v171
	v_sub_f32_e32 v233, v39, v171
	v_sub_f32_e32 v234, v40, v171
	v_sub_f32_e32 v235, v41, v171
	v_sub_f32_e32 v236, v42, v171
	v_sub_f32_e32 v237, v43, v171
	v_sub_f32_e32 v238, v44, v171
	v_sub_f32_e32 v239, v45, v171
	v_sub_f32_e32 v240, v46, v171
	v_sub_f32_e32 v242, v47, v171
	v_sub_f32_e32 v243, v48, v171
	v_sub_f32_e32 v241, v49, v171
	s_waitcnt vmcnt(1)
	ds_write_b128 v125, v[22:25] offset:49152
	s_waitcnt vmcnt(0)
	ds_write_b128 v170, v[26:29]
	v_cmp_gt_u32_e64 s[36:37], 32, v59
	v_add_u32_e32 v121, s61, v61
	v_or3_b32 v112, v112, v18, s59
	v_mov_b64_e32 v[64:65], v[16:17]
	v_mov_b64_e32 v[48:49], v[16:17]
	v_mov_b64_e32 v[32:33], v[16:17]
	s_movk_i32 s59, 0x6000
	v_mov_b64_e32 v[62:63], v[14:15]
	v_mov_b64_e32 v[60:61], v[12:13]
	v_mov_b64_e32 v[58:59], v[10:11]
	v_mov_b64_e32 v[56:57], v[8:9]
	v_mov_b64_e32 v[54:55], v[6:7]
	v_mov_b64_e32 v[52:53], v[4:5]
	v_mov_b64_e32 v[50:51], v[2:3]
	v_mov_b64_e32 v[46:47], v[14:15]
	v_mov_b64_e32 v[44:45], v[12:13]
	v_mov_b64_e32 v[42:43], v[10:11]
	v_mov_b64_e32 v[40:41], v[8:9]
	v_mov_b64_e32 v[38:39], v[6:7]
	v_mov_b64_e32 v[36:37], v[4:5]
	v_mov_b64_e32 v[34:35], v[2:3]
	v_mov_b64_e32 v[30:31], v[14:15]
	v_mov_b64_e32 v[28:29], v[12:13]
	v_mov_b64_e32 v[26:27], v[10:11]
	v_mov_b64_e32 v[24:25], v[8:9]
	v_mov_b64_e32 v[22:23], v[6:7]
	v_mov_b64_e32 v[20:21], v[4:5]
	v_mov_b64_e32 v[18:19], v[2:3]
	s_waitcnt lgkmcnt(0)
	s_barrier
